# mlstm_dpp_scan_plus_fcum_parallel_prefix
# speedup vs baseline: 1.0193x; 1.0089x over previous
; __device__ __forceinline__ void fcum_item(const Params& p, unsigned char* lds, int item) {
;     ...
;   float loc[9]; float s = 0.f;
; #pragma unroll
;   for (int k = 0; k < 9; ++k) { const int t = tid * 9 + k; loc[k] = t < T ? G[(size_t)(b * T + t) * 8 + hh] : 0.f; s += loc[k]; }
;   __syncthreads();
;   part[tid] = s;
;   __syncthreads();
;   float pre = 0.f;
;   for (int i = 0; i < tid; ++i) pre += part[i];
; #pragma unroll
;   for (int k = 0; k < 9; ++k) { const int t = tid * 9 + k; pre += loc[k]; if (t < T) FC[t] = pre; }
.LBB0_1600:
	s_or_b64 exec, exec, s[4:5]
	s_waitcnt vmcnt(0)
	v_add_f32_e32 v11, 0, v6
	v_add_f32_e32 v12, v11, v2
	v_add_f32_e32 v12, v12, v5
	v_add_f32_e32 v12, v12, v3
	v_add_f32_e32 v12, v12, v8
	v_add_f32_e32 v12, v12, v4
	v_add_f32_e32 v12, v12, v9
	v_add_f32_e32 v12, v12, v7
	v_add_f32_e32 v12, v12, v10
	s_waitcnt lgkmcnt(0)
	s_barrier
	v_mov_b32_e32 v14, v12
	s_nop 1
	v_add_f32_dpp v14, v14, v14 row_shr:1 row_mask:0xf bank_mask:0xf
	s_nop 1
	v_add_f32_dpp v14, v14, v14 row_shr:2 row_mask:0xf bank_mask:0xf
	s_nop 1
	v_add_f32_dpp v14, v14, v14 row_shr:4 row_mask:0xf bank_mask:0xf
	s_nop 1
	v_add_f32_dpp v14, v14, v14 row_shr:8 row_mask:0xf bank_mask:0xf
	s_nop 1
	v_add_f32_dpp v14, v14, v14 row_bcast:15 row_mask:0xa bank_mask:0xf
	s_nop 1
	v_add_f32_dpp v14, v14, v14 row_bcast:31 row_mask:0xc bank_mask:0xf
	s_nop 0
	v_readlane_b32 s9, v14, 63
	v_lshrrev_b32_e32 v15, 6, v1
	v_lshlrev_b32_e32 v13, 2, v15
	s_nop 0
	v_mov_b32_e32 v16, s9
	ds_write_b32 v13, v16
	s_waitcnt lgkmcnt(0)
	s_barrier
	v_mov_b32_e32 v13, 0
	ds_read_b128 v[20:23], v13
	ds_read_b128 v[24:27], v13 offset:16
	v_sub_f32_e32 v14, v14, v12
	v_mov_b32_e32 v17, 0
	s_waitcnt lgkmcnt(0)
	v_cmp_lt_u32_e64 s[6:7], 0, v15
	s_nop 1
	v_cndmask_b32_e64 v18, 0, v20, s[6:7]
	v_add_f32_e32 v17, v17, v18
	v_cmp_lt_u32_e64 s[6:7], 1, v15
	s_nop 1
	v_cndmask_b32_e64 v18, 0, v21, s[6:7]
	v_add_f32_e32 v17, v17, v18
	v_cmp_lt_u32_e64 s[6:7], 2, v15
	s_nop 1
	v_cndmask_b32_e64 v18, 0, v22, s[6:7]
	v_add_f32_e32 v17, v17, v18
	v_cmp_lt_u32_e64 s[6:7], 3, v15
	s_nop 1
	v_cndmask_b32_e64 v18, 0, v23, s[6:7]
	v_add_f32_e32 v17, v17, v18
	v_cmp_lt_u32_e64 s[6:7], 4, v15
	s_nop 1
	v_cndmask_b32_e64 v18, 0, v24, s[6:7]
	v_add_f32_e32 v17, v17, v18
	v_cmp_lt_u32_e64 s[6:7], 5, v15
	s_nop 1
	v_cndmask_b32_e64 v18, 0, v25, s[6:7]
	v_add_f32_e32 v17, v17, v18
	v_cmp_lt_u32_e64 s[6:7], 6, v15
	s_nop 1
	v_cndmask_b32_e64 v18, 0, v26, s[6:7]
	v_add_f32_e32 v17, v17, v18
	v_add_f32_e32 v14, v17, v14
	v_add_f32_e32 v11, v6, v14
